# code placement: pad nops pin every hot loop head (4 GEMM K-loops, P2 loop, both attention tile loops) to the baseline object's byte phase mod 64
# baseline (speedup 1.0000x reference)
; template <class Epi, class Sched, bool ALIGN_EPI = false, bool SP2 = false>
; __device__ __forceinline__ void gemm_phase(PG8_LAS unsigned char* lds, const Gemm g, const Sched& S, const Epi& E, const int wave_) {
;     ...
;         const bool has_next = S.next(ui + 1, nxt);
;         const char* nA = has_next ? (const char*)g.A + (size_t)nxt.pm * tstep : cA; const char* nB = has_next ? (const char*)g.Bt + (size_t)nxt.pn * tstep : cB;
;     ...
; #pragma unroll
;         for (int a = 0; a < 2; ++a)
; #pragma unroll
;             for (int b = 0; b < 2; ++b)
; #pragma unroll
;                 for (int m = 0; m < 4; ++m)
; #pragma unroll
;                     for (int n = 0; n < 2; ++n) acc[a][b][m][n] = (f32x4){0.f, 0.f, 0.f, 0.f};
;         cur = nxt; cA = nA; cB = nB; ++ui;
.LBB0_128:
	s_ashr_i32 s39, s38, 31
	s_lshl_b64 s[22:23], s[38:39], 20
	v_readlane_b32 s24, v248, 27
	v_readlane_b32 s25, v248, 28
	s_add_u32 s40, s24, s22
	s_addc_u32 s41, s25, s23
	s_and_b64 s[22:23], s[16:17], exec
	s_cselect_b32 s19, s41, s47
	s_cselect_b32 s39, s40, s46
	s_ashr_i32 s37, s36, 31
	s_lshl_b64 s[22:23], s[36:37], 20
	v_readlane_b32 s24, v248, 25
	v_readlane_b32 s25, v248, 26
	s_add_u32 s42, s24, s22
	s_addc_u32 s43, s25, s23
	s_and_b64 s[22:23], s[16:17], exec
	s_cselect_b32 s37, s43, s49
	s_cselect_b32 vcc_lo, s42, s48
	s_add_u32 s46, s46, 0x80080
	s_addc_u32 s47, s47, 0
	s_add_u32 vcc_hi, s48, 0x100
	v_mov_b32_e32 v0, 0
	s_addc_u32 s97, s49, 0
	s_mov_b32 s22, -2
	v_mov_b32_e32 v1, 0
	v_mov_b64_e32 v[2:3], 0
	v_mov_b64_e32 v[4:5], 0
	v_mov_b64_e32 v[6:7], 0
	v_mov_b64_e32 v[8:9], 0
	v_mov_b64_e32 v[10:11], 0
	v_mov_b64_e32 v[12:13], 0
	v_mov_b64_e32 v[14:15], 0
	v_mov_b64_e32 v[16:17], 0
	v_mov_b64_e32 v[18:19], 0
	v_mov_b64_e32 v[20:21], 0
	v_mov_b64_e32 v[22:23], 0
	v_mov_b64_e32 v[24:25], 0
	v_mov_b64_e32 v[26:27], 0
	v_mov_b64_e32 v[28:29], 0
	v_mov_b64_e32 v[30:31], 0
	v_mov_b64_e32 v[32:33], 0
	v_mov_b64_e32 v[34:35], 0
	v_mov_b64_e32 v[36:37], 0
	v_mov_b64_e32 v[38:39], 0
	v_mov_b64_e32 v[40:41], 0
	v_mov_b64_e32 v[42:43], 0
	v_mov_b64_e32 v[44:45], 0
	v_mov_b64_e32 v[46:47], 0
	v_mov_b64_e32 v[48:49], 0
	v_mov_b64_e32 v[50:51], 0
	v_mov_b64_e32 v[52:53], 0
	v_mov_b64_e32 v[54:55], 0
	v_mov_b64_e32 v[56:57], 0
	v_mov_b64_e32 v[58:59], 0
	v_mov_b64_e32 v[60:61], 0
	v_mov_b64_e32 v[62:63], 0
	v_mov_b64_e32 v[64:65], 0
	v_mov_b64_e32 v[66:67], 0
	v_mov_b64_e32 v[68:69], 0
	v_mov_b64_e32 v[70:71], 0
	v_mov_b64_e32 v[72:73], 0
	v_mov_b64_e32 v[74:75], 0
	v_mov_b64_e32 v[76:77], 0
	v_mov_b64_e32 v[78:79], 0
	v_mov_b64_e32 v[80:81], 0
	v_mov_b64_e32 v[82:83], 0
	v_mov_b64_e32 v[84:85], 0
	v_mov_b64_e32 v[86:87], 0
	v_mov_b64_e32 v[88:89], 0
	v_mov_b64_e32 v[90:91], 0
	v_mov_b64_e32 v[92:93], 0
	v_mov_b64_e32 v[94:95], 0
	v_mov_b64_e32 v[96:97], 0
	v_mov_b64_e32 v[98:99], 0
	v_mov_b64_e32 v[100:101], 0
	v_mov_b64_e32 v[102:103], 0
	v_mov_b64_e32 v[104:105], 0
	v_mov_b64_e32 v[106:107], 0
	v_mov_b64_e32 v[108:109], 0
	v_mov_b64_e32 v[110:111], 0
	v_mov_b64_e32 v[112:113], 0
	v_mov_b64_e32 v[114:115], 0
	v_mov_b64_e32 v[116:117], 0
	v_mov_b64_e32 v[118:119], 0
	v_mov_b64_e32 v[120:121], 0
	v_mov_b64_e32 v[122:123], 0
	v_mov_b64_e32 v[124:125], 0
	v_mov_b64_e32 v[126:127], 0
	s_nop 0
	s_nop 0
	s_nop 0
	s_nop 0
	s_nop 0
	s_nop 0
	s_nop 0
	s_nop 0
	s_nop 0
	s_nop 0
	s_nop 0
	s_nop 0
	s_nop 0
	s_nop 0
	s_nop 0

; #define LAS __attribute__((address_space(3)))
; __device__ __forceinline__ s16x4 vtr(const LAS unsigned char* p) { return __builtin_bit_cast(s16x4, __builtin_amdgcn_ds_read_tr16_b64_v4i16((LAS s16x4*)p)); }
; __device__ __forceinline__ int crow(int r, int hi) { return (r & 3) + 8 * (r >> 2) + 4 * hi; }
; #define lane lane_id()
; __device__ __forceinline__ void mix_unit(LAS unsigned char* lds, const int wid, int n, int g, const bf16_t* __restrict__ UZ, const bf16_t* __restrict__ V, const float* __restrict__ vss, ...
;     ...
;     {
;         const LAS unsigned char* vimg = lds + 32768 + (wid >> 2) * 32768;
;         const unsigned cblk = wid & 3, qa = (lane & 15) >> 2, blk = (lane >> 4) & 1, pp = lane & 3;
; #pragma unroll
;         for (int ks = 0; ks < 8; ++ks) {
;             const s16x4 lo = vtr(vimg + off_b(16 * ks + 8 * hi + qa, 4 * cblk + 2 * blk + (pp >> 1)) + 8 * (pp & 1));
;             const s16x4 hh = vtr(vimg + off_b(16 * ks + 8 * hi + 4 + qa, 4 * cblk + 2 * blk + (pp >> 1)) + 8 * (pp & 1));
;             const bf16x8 vf = (bf16x8){lo[0], lo[1], lo[2], lo[3], hh[0], hh[1], hh[2], hh[3]};
; #pragma unroll
;             for (int i = 0; i < 4; ++i) if (ks <= 2 * i + 1) {
;                 const bf16x8 af = *(const LAS bf16x8*)(lds + off_b(32 * i + r32, 2 * ks + hi));
;                 acc[i] = __builtin_amdgcn_mfma_f32_32x32x16_bf16(af, vf, acc[i], 0, 0, 0);
;             }
;         }
;     }
;     __syncthreads();
;     {
;         LAS float* mx = (LAS float*)lds;
;         const int c = 128 * (wid >> 2) + 32 * (wid & 3) + r32;
; #pragma unroll
;         for (int i = 0; i < 4; ++i)
; #pragma unroll
;             for (int r = 0; r < 16; ++r) mx[(32 * i + crow(r, hi)) * 256 + c] = acc[i][r];
;     }
;     __syncthreads();
.Lp2_mfma:
	ds_read_b64_tr_b16 v[0:1], v218 offset:32768
	ds_read_b64_tr_b16 v[2:3], v219 offset:33792
	ds_read_b128 v[4:7], v220
	s_waitcnt lgkmcnt(0)
	v_mfma_f32_32x32x16_bf16 v[48:63], v[4:7], v[0:3], 0
	ds_read_b128 v[4:7], v220 offset:8192
	s_lshl_b32 s72, s97, 8
	s_lshl_b32 s82, s72, 2
	s_mov_b32 s83, s77
	s_waitcnt lgkmcnt(0)
	v_mfma_f32_32x32x16_bf16 v[32:47], v[4:7], v[0:3], 0
	ds_read_b128 v[4:7], v220 offset:16384
	s_waitcnt lgkmcnt(0)
	v_mfma_f32_32x32x16_bf16 v[16:31], v[4:7], v[0:3], 0
	ds_read_b128 v[4:7], v220 offset:24576
	ds_read_b64_tr_b16 v[236:237], v218 offset:36864
	ds_read_b64_tr_b16 v[238:239], v219 offset:37888
	ds_read_b128 v[240:243], v221
	s_waitcnt lgkmcnt(0)
	v_mfma_f32_32x32x16_bf16 v[48:63], v[240:243], v[236:239], v[48:63]
	ds_read_b128 v[240:243], v221 offset:8192
	s_waitcnt lgkmcnt(0)
	v_mfma_f32_32x32x16_bf16 v[32:47], v[240:243], v[236:239], v[32:47]
	ds_read_b128 v[240:243], v221 offset:16384
	s_waitcnt lgkmcnt(0)
	v_mfma_f32_32x32x16_bf16 v[16:31], v[240:243], v[236:239], v[16:31]
	ds_read_b128 v[240:243], v221 offset:24576
	v_mfma_f32_32x32x16_bf16 v[0:15], v[4:7], v[0:3], 0
	s_waitcnt lgkmcnt(0)
	v_mfma_f32_32x32x16_bf16 v[0:15], v[240:243], v[236:239], v[0:15]
	ds_read_b64_tr_b16 v[236:237], v218 offset:40960
	ds_read_b64_tr_b16 v[238:239], v219 offset:41984
	ds_read_b128 v[240:243], v222 offset:8192
	s_waitcnt lgkmcnt(0)
	v_mfma_f32_32x32x16_bf16 v[32:47], v[240:243], v[236:239], v[32:47]
	ds_read_b128 v[240:243], v222 offset:16384
	s_waitcnt lgkmcnt(0)
	v_mfma_f32_32x32x16_bf16 v[16:31], v[240:243], v[236:239], v[16:31]
	ds_read_b128 v[240:243], v222 offset:24576
	s_waitcnt lgkmcnt(0)
	v_mfma_f32_32x32x16_bf16 v[0:15], v[240:243], v[236:239], v[0:15]
	ds_read_b64_tr_b16 v[236:237], v218 offset:45056
	ds_read_b64_tr_b16 v[238:239], v219 offset:46080
	ds_read_b128 v[240:243], v223 offset:8192
	s_waitcnt lgkmcnt(0)
	v_mfma_f32_32x32x16_bf16 v[32:47], v[240:243], v[236:239], v[32:47]
	ds_read_b128 v[240:243], v223 offset:16384
	s_waitcnt lgkmcnt(0)
	v_mfma_f32_32x32x16_bf16 v[16:31], v[240:243], v[236:239], v[16:31]
	ds_read_b128 v[240:243], v223 offset:24576
	s_waitcnt lgkmcnt(0)
	v_mfma_f32_32x32x16_bf16 v[0:15], v[240:243], v[236:239], v[0:15]
	ds_read_b64_tr_b16 v[236:237], v218 offset:49152
	ds_read_b64_tr_b16 v[238:239], v219 offset:50176
	ds_read_b128 v[240:243], v224 offset:16384
	s_waitcnt lgkmcnt(0)
	v_mfma_f32_32x32x16_bf16 v[16:31], v[240:243], v[236:239], v[16:31]
	ds_read_b128 v[240:243], v224 offset:24576
	s_waitcnt lgkmcnt(0)
	v_mfma_f32_32x32x16_bf16 v[0:15], v[240:243], v[236:239], v[0:15]
	ds_read_b64_tr_b16 v[236:237], v218 offset:53248
	ds_read_b64_tr_b16 v[238:239], v219 offset:54272
	ds_read_b128 v[240:243], v225 offset:16384
	s_waitcnt lgkmcnt(0)
	v_mfma_f32_32x32x16_bf16 v[16:31], v[240:243], v[236:239], v[16:31]
	ds_read_b128 v[240:243], v225 offset:24576
	s_waitcnt lgkmcnt(0)
	v_mfma_f32_32x32x16_bf16 v[0:15], v[240:243], v[236:239], v[0:15]
	ds_read_b64_tr_b16 v[236:237], v218 offset:57344
	ds_read_b64_tr_b16 v[238:239], v219 offset:58368
	ds_read_b128 v[240:243], v226 offset:24576
	s_waitcnt lgkmcnt(0)
	v_mfma_f32_32x32x16_bf16 v[0:15], v[240:243], v[236:239], v[0:15]
	ds_read_b64_tr_b16 v[236:237], v218 offset:61440
	ds_read_b64_tr_b16 v[238:239], v219 offset:62464
	ds_read_b128 v[240:243], v227 offset:24576
	s_waitcnt lgkmcnt(0)
	s_barrier
	v_mfma_f32_32x32x16_bf16 v[0:15], v[240:243], v[236:239], v[0:15]
	ds_write2st64_b32 v171, v48, v49 offset1:4
	ds_write2st64_b32 v171, v50, v51 offset0:8 offset1:12
	ds_write2st64_b32 v171, v52, v53 offset0:32 offset1:36
	ds_write2st64_b32 v171, v54, v55 offset0:40 offset1:44
	ds_write2st64_b32 v171, v56, v57 offset0:64 offset1:68
	ds_write2st64_b32 v171, v58, v59 offset0:72 offset1:76
	ds_write2st64_b32 v171, v60, v61 offset0:96 offset1:100
	ds_write2st64_b32 v171, v62, v63 offset0:104 offset1:108
	ds_write2st64_b32 v171, v32, v33 offset0:128 offset1:132
	ds_write2st64_b32 v171, v34, v35 offset0:136 offset1:140
	ds_write2st64_b32 v171, v36, v37 offset0:160 offset1:164
	ds_write2st64_b32 v171, v38, v39 offset0:168 offset1:172
	ds_write2st64_b32 v171, v40, v41 offset0:192 offset1:196
	ds_write2st64_b32 v171, v42, v43 offset0:200 offset1:204
	ds_write2st64_b32 v171, v44, v45 offset0:224 offset1:228
	ds_write2st64_b32 v171, v46, v47 offset0:232 offset1:236
	ds_write_b32 v172, v16
	ds_write_b32 v173, v17
	ds_write_b32 v174, v18
	ds_write_b32 v175, v19
	ds_write_b32 v176, v20
	ds_write_b32 v177, v21
	ds_write_b32 v178, v22
	ds_write_b32 v179, v23
	ds_write_b32 v180, v24
	ds_write_b32 v181, v25
	ds_write_b32 v182, v26
	ds_write_b32 v183, v27
	ds_write_b32 v184, v28
	ds_write_b32 v185, v29
	ds_write_b32 v186, v30
	ds_write_b32 v187, v31
	ds_write_b32 v188, v0
	ds_write_b32 v189, v1
	ds_write_b32 v190, v2
	ds_write_b32 v191, v3
	ds_write_b32 v192, v4
	ds_write_b32 v193, v5
	ds_write_b32 v194, v6
	ds_write_b32 v196, v7
	ds_write_b32 v197, v8
	ds_write_b32 v198, v9
	ds_write_b32 v199, v10
	ds_write_b32 v200, v11
	ds_write_b32 v201, v12
	ds_write_b32 v202, v13
	ds_write_b32 v203, v14
	ds_write_b32 v204, v15
	v_lshl_add_u64 v[4:5], v[142:143], 0, s[82:83]
	s_waitcnt lgkmcnt(0)
	s_barrier
; #define LAS __attribute__((address_space(3)))
; __device__ __forceinline__ unsigned pk_bf16(float lo, float hi) { return pg8::cvt_pk_bf16(lo, hi); }
; __device__ __forceinline__ float bf_lo(unsigned w) { return __uint_as_float(w << 16); }
; __device__ __forceinline__ float bf_hi(unsigned w) { return __uint_as_float(w & 0xffff0000u); }
; #define tid tid_of(wave)
; __device__ __forceinline__ void mix_unit(LAS unsigned char* lds, const int wid, int n, int g, const bf16_t* __restrict__ UZ, const bf16_t* __restrict__ V, const float* __restrict__ vss, ...
;     ...
;     {
;         const f32x4 g0 = *(const f32x4*)(vg + g * GDIM + cc * 8), g1 = *(const f32x4*)(vg + g * GDIM + cc * 8 + 4);
;         float bb[8];
; #pragma unroll
;         for (int i = 0; i < 8; ++i) bb[i] = b_s[g * CHUNK + (tid >> 5) + 16 * i];
; #pragma unroll
;         for (int i = 0; i < 8; ++i) { const int t = (tid >> 5) + 16 * i;
;             const f32x4 m0 = *(const LAS f32x4*)(lds + (t * 256 + cc * 8) * 4), m1 = *(const LAS f32x4*)(lds + (t * 256 + cc * 8 + 4) * 4);
;             float y[8];
;             y[0] = bf_lo(uu[i].x) * (m0[0] * g0[0] + bb[i]); y[1] = bf_hi(uu[i].x) * (m0[1] * g0[1] + bb[i]);
;             y[2] = bf_lo(uu[i].y) * (m0[2] * g0[2] + bb[i]); y[3] = bf_hi(uu[i].y) * (m0[3] * g0[3] + bb[i]);
;             y[4] = bf_lo(uu[i].z) * (m1[0] * g1[0] + bb[i]); y[5] = bf_hi(uu[i].z) * (m1[1] * g1[1] + bb[i]);
;             y[6] = bf_lo(uu[i].w) * (m1[2] * g1[2] + bb[i]); y[7] = bf_hi(uu[i].w) * (m1[3] * g1[3] + bb[i]);
;             u32x4 w; w.x = pk_bf16(y[0], y[1]); w.y = pk_bf16(y[2], y[3]); w.z = pk_bf16(y[4], y[5]); w.w = pk_bf16(y[6], y[7]);
;             *(u32x4*)(Y + (row0 + t) * GW + g * GDIM + cc * 8) = w; }
;     }
	s_waitcnt vmcnt(0)
	global_load_dwordx4 v[0:3], v[4:5], off offset:16
	s_nop 0
	global_load_dwordx4 v[4:7], v[4:5], off
	v_add_u32_e32 v8, s76, v96
	v_readlane_b32 s80, v248, 6
	v_ashrrev_i32_e32 v9, 31, v8
	v_readlane_b32 s90, v248, 16
	v_readlane_b32 s91, v248, 17
	v_lshlrev_b32_e32 v26, 16, v92
	s_lshl_b32 s76, s72, 1
	v_lshl_add_u64 v[8:9], v[8:9], 2, s[90:91]
	global_load_dword v18, v[8:9], off
	global_load_dword v19, v[8:9], off offset:64
	global_load_dword v20, v[8:9], off offset:128
	global_load_dword v21, v[8:9], off offset:192
	global_load_dword v22, v[8:9], off offset:256
	global_load_dword v23, v[8:9], off offset:320
	global_load_dword v24, v[8:9], off offset:384
	global_load_dword v25, v[8:9], off offset:448
	ds_read_b128 v[10:13], v228
	ds_read_b128 v[14:17], v228 offset:16
	v_lshl_add_u64 v[8:9], v[144:145], 0, s[76:77]
	v_readlane_b32 s88, v248, 14
	v_readlane_b32 s89, v248, 15
	v_readlane_b32 s88, v248, 35
	s_add_i32 s71, s71, s88
	v_readlane_b32 s89, v248, 36
	s_cmpk_lt_i32 s71, 0x400
	v_readlane_b32 s81, v248, 7
	v_readlane_b32 s82, v248, 8
	v_readlane_b32 s83, v248, 9
	v_readlane_b32 s84, v248, 10
	v_readlane_b32 s85, v248, 11
	v_readlane_b32 s86, v248, 12
	v_readlane_b32 s87, v248, 13
	v_readlane_b32 s92, v248, 18
	v_readlane_b32 s93, v248, 19
	v_readlane_b32 s94, v248, 20
	v_readlane_b32 s95, v248, 21
	s_waitcnt vmcnt(7) lgkmcnt(0)
	v_fma_f32 v14, v0, v14, v18
	v_fma_f32 v10, v4, v10, v18
	v_mul_f32_e32 v10, v10, v26
	v_and_b32_e32 v26, 0xffff0000, v92
	v_fma_f32 v11, v5, v11, v18
	v_mul_f32_e32 v11, v11, v26
	v_lshlrev_b32_e32 v26, 16, v93
	v_fma_f32 v12, v6, v12, v18
	v_mul_f32_e32 v12, v12, v26
	v_and_b32_e32 v26, 0xffff0000, v93
	v_fma_f32 v13, v7, v13, v18
	v_mul_f32_e32 v13, v13, v26
	v_lshlrev_b32_e32 v26, 16, v94
	v_mul_f32_e32 v14, v14, v26
	v_and_b32_e32 v26, 0xffff0000, v94
	v_fma_f32 v15, v1, v15, v18
	v_mul_f32_e32 v15, v15, v26
	v_lshlrev_b32_e32 v26, 16, v95
	v_fma_f32 v16, v2, v16, v18
	v_mul_f32_e32 v16, v16, v26
	v_and_b32_e32 v26, 0xffff0000, v95
	v_fmac_f32_e32 v18, v3, v17
	v_cvt_pk_bf16_f32 v10, v10, v11
	v_cvt_pk_bf16_f32 v11, v12, v13
	v_cvt_pk_bf16_f32 v12, v14, v15
	v_lshl_add_u64 v[14:15], v[8:9], 0, v[162:163]
	v_mul_f32_e32 v17, v18, v26
	v_cvt_pk_bf16_f32 v13, v16, v17
	global_store_dwordx4 v[14:15], v[10:13], off sc1
	ds_read_b128 v[10:13], v229
	ds_read_b128 v[14:17], v229 offset:16
	v_lshlrev_b32_e32 v18, 16, v88
	s_waitcnt vmcnt(7) lgkmcnt(1)
	v_fma_f32 v10, v4, v10, v19
	v_mul_f32_e32 v10, v10, v18
	v_and_b32_e32 v18, 0xffff0000, v88
	v_fma_f32 v11, v5, v11, v19
	v_mul_f32_e32 v11, v11, v18
	v_lshlrev_b32_e32 v18, 16, v89
	v_fma_f32 v12, v6, v12, v19
	v_mul_f32_e32 v12, v12, v18
	v_and_b32_e32 v18, 0xffff0000, v89
	v_fma_f32 v13, v7, v13, v19
	v_mul_f32_e32 v13, v13, v18
	v_lshlrev_b32_e32 v18, 16, v90
	s_waitcnt lgkmcnt(0)
	v_fma_f32 v14, v0, v14, v19
	v_mul_f32_e32 v14, v14, v18
	v_and_b32_e32 v18, 0xffff0000, v90
	v_fma_f32 v15, v1, v15, v19
	v_mul_f32_e32 v15, v15, v18
	v_lshlrev_b32_e32 v18, 16, v91
	v_fma_f32 v16, v2, v16, v19
	v_mul_f32_e32 v16, v16, v18
	v_and_b32_e32 v18, 0xffff0000, v91
	v_fmac_f32_e32 v19, v3, v17
	v_cvt_pk_bf16_f32 v10, v10, v11
	v_cvt_pk_bf16_f32 v11, v12, v13
	v_cvt_pk_bf16_f32 v12, v14, v15
	v_lshl_add_u64 v[14:15], v[8:9], 0, v[160:161]
	v_mul_f32_e32 v17, v19, v18
	v_cvt_pk_bf16_f32 v13, v16, v17
	global_store_dwordx4 v[14:15], v[10:13], off sc1
	ds_read_b128 v[10:13], v230
	ds_read_b128 v[14:17], v230 offset:16
	v_lshlrev_b32_e32 v18, 16, v84
	s_waitcnt vmcnt(7) lgkmcnt(1)
	v_fma_f32 v10, v4, v10, v20
	v_mul_f32_e32 v10, v10, v18
	v_and_b32_e32 v18, 0xffff0000, v84
	v_fma_f32 v11, v5, v11, v20
	v_mul_f32_e32 v11, v11, v18
	v_lshlrev_b32_e32 v18, 16, v85
	v_fma_f32 v12, v6, v12, v20
	v_mul_f32_e32 v12, v12, v18
	v_and_b32_e32 v18, 0xffff0000, v85
	v_fma_f32 v13, v7, v13, v20
	v_mul_f32_e32 v13, v13, v18
	v_lshlrev_b32_e32 v18, 16, v86
	s_waitcnt lgkmcnt(0)
	v_fma_f32 v14, v0, v14, v20
	v_mul_f32_e32 v14, v14, v18
	v_and_b32_e32 v18, 0xffff0000, v86
	v_fma_f32 v15, v1, v15, v20
	v_mul_f32_e32 v15, v15, v18
	v_lshlrev_b32_e32 v18, 16, v87
	v_fma_f32 v16, v2, v16, v20
	v_mul_f32_e32 v16, v16, v18
	v_and_b32_e32 v18, 0xffff0000, v87
	v_fmac_f32_e32 v20, v3, v17
	v_cvt_pk_bf16_f32 v10, v10, v11
	v_cvt_pk_bf16_f32 v11, v12, v13
	v_cvt_pk_bf16_f32 v12, v14, v15
	v_lshl_add_u64 v[14:15], v[8:9], 0, v[158:159]
	v_mul_f32_e32 v17, v20, v18
	v_cvt_pk_bf16_f32 v13, v16, v17
	global_store_dwordx4 v[14:15], v[10:13], off sc1
	ds_read_b128 v[10:13], v231
	ds_read_b128 v[14:17], v231 offset:16
	v_lshlrev_b32_e32 v18, 16, v80
	s_waitcnt vmcnt(7) lgkmcnt(1)
	v_fma_f32 v10, v4, v10, v21
	v_mul_f32_e32 v10, v10, v18
	v_and_b32_e32 v18, 0xffff0000, v80
	v_fma_f32 v11, v5, v11, v21
	v_mul_f32_e32 v11, v11, v18
	v_lshlrev_b32_e32 v18, 16, v81
	v_fma_f32 v12, v6, v12, v21
	v_mul_f32_e32 v12, v12, v18
	v_and_b32_e32 v18, 0xffff0000, v81
	v_fma_f32 v13, v7, v13, v21
	v_mul_f32_e32 v13, v13, v18
	v_lshlrev_b32_e32 v18, 16, v82
	s_waitcnt lgkmcnt(0)
; #define LAS __attribute__((address_space(3)))
; __device__ __forceinline__ unsigned pk_bf16(float lo, float hi) { return pg8::cvt_pk_bf16(lo, hi); }
; __device__ __forceinline__ float bf_lo(unsigned w) { return __uint_as_float(w << 16); }
; __device__ __forceinline__ float bf_hi(unsigned w) { return __uint_as_float(w & 0xffff0000u); }
; #define tid tid_of(wave)
; __device__ __forceinline__ void mix_unit(LAS unsigned char* lds, const int wid, int n, int g, const bf16_t* __restrict__ UZ, const bf16_t* __restrict__ V, const float* __restrict__ vss, ...
;     ...
;         for (int i = 0; i < 8; ++i) { const int t = (tid >> 5) + 16 * i;
;             const f32x4 m0 = *(const LAS f32x4*)(lds + (t * 256 + cc * 8) * 4), m1 = *(const LAS f32x4*)(lds + (t * 256 + cc * 8 + 4) * 4);
;             float y[8];
;             y[0] = bf_lo(uu[i].x) * (m0[0] * g0[0] + bb[i]); y[1] = bf_hi(uu[i].x) * (m0[1] * g0[1] + bb[i]);
;             y[2] = bf_lo(uu[i].y) * (m0[2] * g0[2] + bb[i]); y[3] = bf_hi(uu[i].y) * (m0[3] * g0[3] + bb[i]);
;             y[4] = bf_lo(uu[i].z) * (m1[0] * g1[0] + bb[i]); y[5] = bf_hi(uu[i].z) * (m1[1] * g1[1] + bb[i]);
;             y[6] = bf_lo(uu[i].w) * (m1[2] * g1[2] + bb[i]); y[7] = bf_hi(uu[i].w) * (m1[3] * g1[3] + bb[i]);
;             u32x4 w; w.x = pk_bf16(y[0], y[1]); w.y = pk_bf16(y[2], y[3]); w.z = pk_bf16(y[4], y[5]); w.w = pk_bf16(y[6], y[7]);
;             *(u32x4*)(Y + (row0 + t) * GW + g * GDIM + cc * 8) = w; }
;     }
;     __syncthreads();
; __global__ void __launch_bounds__(NWAVES * 64, 2) fwd_kernel(Args a) {
;     ...
;         for (int it = vcu; it < (NTOK / CHUNK) * NGRP; it += G) mix_unit(lds, wave, it >> 4, it & 15, U, V, VSS, a_w_s, a_b_s, a_vg, Y);
	v_fma_f32 v14, v0, v14, v21
	v_mul_f32_e32 v14, v14, v18
	v_and_b32_e32 v18, 0xffff0000, v82
	v_fma_f32 v15, v1, v15, v21
	v_mul_f32_e32 v15, v15, v18
	v_lshlrev_b32_e32 v18, 16, v83
	v_fma_f32 v16, v2, v16, v21
	v_mul_f32_e32 v16, v16, v18
	v_and_b32_e32 v18, 0xffff0000, v83
	v_fmac_f32_e32 v21, v3, v17
	v_cvt_pk_bf16_f32 v10, v10, v11
	v_cvt_pk_bf16_f32 v11, v12, v13
	v_cvt_pk_bf16_f32 v12, v14, v15
	v_lshl_add_u64 v[14:15], v[8:9], 0, v[156:157]
	v_mul_f32_e32 v17, v21, v18
	v_cvt_pk_bf16_f32 v13, v16, v17
	global_store_dwordx4 v[14:15], v[10:13], off sc1
	ds_read_b128 v[10:13], v232
	ds_read_b128 v[14:17], v232 offset:16
	v_lshlrev_b32_e32 v18, 16, v76
	s_waitcnt vmcnt(7) lgkmcnt(1)
	v_fma_f32 v10, v4, v10, v22
	v_mul_f32_e32 v10, v10, v18
	v_and_b32_e32 v18, 0xffff0000, v76
	v_fma_f32 v11, v5, v11, v22
	v_mul_f32_e32 v11, v11, v18
	v_lshlrev_b32_e32 v18, 16, v77
	v_fma_f32 v12, v6, v12, v22
	v_mul_f32_e32 v12, v12, v18
	v_and_b32_e32 v18, 0xffff0000, v77
	v_fma_f32 v13, v7, v13, v22
	v_mul_f32_e32 v13, v13, v18
	v_lshlrev_b32_e32 v18, 16, v78
	s_waitcnt lgkmcnt(0)
	v_fma_f32 v14, v0, v14, v22
	v_mul_f32_e32 v14, v14, v18
	v_and_b32_e32 v18, 0xffff0000, v78
	v_fma_f32 v15, v1, v15, v22
	v_mul_f32_e32 v15, v15, v18
	v_lshlrev_b32_e32 v18, 16, v79
	v_fma_f32 v16, v2, v16, v22
	v_mul_f32_e32 v16, v16, v18
	v_and_b32_e32 v18, 0xffff0000, v79
	v_fmac_f32_e32 v22, v3, v17
	v_cvt_pk_bf16_f32 v10, v10, v11
	v_cvt_pk_bf16_f32 v11, v12, v13
	v_cvt_pk_bf16_f32 v12, v14, v15
	v_lshl_add_u64 v[14:15], v[8:9], 0, v[154:155]
	v_mul_f32_e32 v17, v22, v18
	v_cvt_pk_bf16_f32 v13, v16, v17
	global_store_dwordx4 v[14:15], v[10:13], off sc1
	ds_read_b128 v[10:13], v233
	ds_read_b128 v[14:17], v233 offset:16
	v_lshlrev_b32_e32 v18, 16, v72
	s_waitcnt vmcnt(7) lgkmcnt(1)
	v_fma_f32 v10, v4, v10, v23
	v_mul_f32_e32 v10, v10, v18
	v_and_b32_e32 v18, 0xffff0000, v72
	v_fma_f32 v11, v5, v11, v23
	v_mul_f32_e32 v11, v11, v18
	v_lshlrev_b32_e32 v18, 16, v73
	v_fma_f32 v12, v6, v12, v23
	v_mul_f32_e32 v12, v12, v18
	v_and_b32_e32 v18, 0xffff0000, v73
	v_fma_f32 v13, v7, v13, v23
	v_mul_f32_e32 v13, v13, v18
	v_lshlrev_b32_e32 v18, 16, v74
	s_waitcnt lgkmcnt(0)
	v_fma_f32 v14, v0, v14, v23
	v_mul_f32_e32 v14, v14, v18
	v_and_b32_e32 v18, 0xffff0000, v74
	v_fma_f32 v15, v1, v15, v23
	v_mul_f32_e32 v15, v15, v18
	v_lshlrev_b32_e32 v18, 16, v75
	v_fma_f32 v16, v2, v16, v23
	v_mul_f32_e32 v16, v16, v18
	v_and_b32_e32 v18, 0xffff0000, v75
	v_fmac_f32_e32 v23, v3, v17
	v_cvt_pk_bf16_f32 v10, v10, v11
	v_cvt_pk_bf16_f32 v11, v12, v13
	v_cvt_pk_bf16_f32 v12, v14, v15
	v_lshl_add_u64 v[14:15], v[8:9], 0, v[150:151]
	v_mul_f32_e32 v17, v23, v18
	v_cvt_pk_bf16_f32 v13, v16, v17
	global_store_dwordx4 v[14:15], v[10:13], off sc1
	ds_read_b128 v[10:13], v234
	ds_read_b128 v[14:17], v234 offset:16
	v_lshlrev_b32_e32 v18, 16, v68
	s_waitcnt vmcnt(7) lgkmcnt(1)
	v_fma_f32 v10, v4, v10, v24
	v_mul_f32_e32 v10, v10, v18
	v_and_b32_e32 v18, 0xffff0000, v68
	v_fma_f32 v11, v5, v11, v24
	v_mul_f32_e32 v11, v11, v18
	v_lshlrev_b32_e32 v18, 16, v69
	v_fma_f32 v12, v6, v12, v24
	v_mul_f32_e32 v12, v12, v18
	v_and_b32_e32 v18, 0xffff0000, v69
	v_fma_f32 v13, v7, v13, v24
	v_mul_f32_e32 v13, v13, v18
	v_lshlrev_b32_e32 v18, 16, v70
	s_waitcnt lgkmcnt(0)
	v_fma_f32 v14, v0, v14, v24
	v_mul_f32_e32 v14, v14, v18
	v_and_b32_e32 v18, 0xffff0000, v70
	v_fma_f32 v15, v1, v15, v24
	v_mul_f32_e32 v15, v15, v18
	v_lshlrev_b32_e32 v18, 16, v71
	v_fma_f32 v16, v2, v16, v24
	v_mul_f32_e32 v16, v16, v18
	v_and_b32_e32 v18, 0xffff0000, v71
	v_fmac_f32_e32 v24, v3, v17
	v_cvt_pk_bf16_f32 v10, v10, v11
	v_cvt_pk_bf16_f32 v11, v12, v13
	v_cvt_pk_bf16_f32 v12, v14, v15
	v_lshl_add_u64 v[14:15], v[8:9], 0, v[148:149]
	v_mul_f32_e32 v17, v24, v18
	v_cvt_pk_bf16_f32 v13, v16, v17
	global_store_dwordx4 v[14:15], v[10:13], off sc1
	ds_read_b128 v[10:13], v235
	ds_read_b128 v[14:17], v235 offset:16
	v_lshlrev_b32_e32 v18, 16, v64
	s_waitcnt vmcnt(7) lgkmcnt(1)
	v_fma_f32 v4, v4, v10, v25
	v_and_b32_e32 v10, 0xffff0000, v64
	v_fma_f32 v5, v5, v11, v25
	v_mul_f32_e32 v5, v5, v10
	v_lshlrev_b32_e32 v10, 16, v65
	v_fma_f32 v6, v6, v12, v25
	v_mul_f32_e32 v6, v6, v10
	v_and_b32_e32 v10, 0xffff0000, v65
	v_fma_f32 v7, v7, v13, v25
	v_mul_f32_e32 v7, v7, v10
	v_lshlrev_b32_e32 v10, 16, v66
	s_waitcnt lgkmcnt(0)
	v_fma_f32 v0, v0, v14, v25
	v_mul_f32_e32 v10, v0, v10
	v_and_b32_e32 v0, 0xffff0000, v66
	v_fma_f32 v1, v1, v15, v25
	v_mul_f32_e32 v11, v1, v0
	v_lshlrev_b32_e32 v0, 16, v67
	v_fma_f32 v1, v2, v16, v25
	v_mul_f32_e32 v4, v4, v18
	v_mul_f32_e32 v12, v1, v0
	v_and_b32_e32 v0, 0xffff0000, v67
	v_fmac_f32_e32 v25, v3, v17
	v_mul_f32_e32 v3, v25, v0
	v_cvt_pk_bf16_f32 v0, v4, v5
	v_lshl_add_u64 v[4:5], v[8:9], 0, v[146:147]
	v_cvt_pk_bf16_f32 v1, v6, v7
	v_cvt_pk_bf16_f32 v2, v10, v11
	v_cvt_pk_bf16_f32 v3, v12, v3
	global_store_dwordx4 v[4:5], v[0:3], off sc1
	s_barrier
	s_cbranch_scc0 .LBB0_331
	s_nop 0
	s_nop 0
	s_nop 0

; template <class Epi, class Sched, bool ALIGN_EPI = false, bool SP2 = false>
; __device__ __forceinline__ void gemm_phase(PG8_LAS unsigned char* lds, const Gemm g, const Sched& S, const Epi& E, const int wave_) {
;     ...
;         const bool has_next = S.next(ui + 1, nxt);
;         const char* nA = has_next ? (const char*)g.A + (size_t)nxt.pm * tstep : cA; const char* nB = has_next ? (const char*)g.Bt + (size_t)nxt.pn * tstep : cB;
;     ...
; #pragma unroll
;         for (int a = 0; a < 2; ++a)
; #pragma unroll
;             for (int b = 0; b < 2; ++b)
; #pragma unroll
;                 for (int m = 0; m < 4; ++m)
; #pragma unroll
;                     for (int n = 0; n < 2; ++n) acc[a][b][m][n] = (f32x4){0.f, 0.f, 0.f, 0.f};
;         cur = nxt; cA = nA; cB = nB; ++ui;
.LBB0_401:
	s_ashr_i32 s19, s18, 31
	s_lshl_b64 s[20:21], s[18:19], 21
	v_readlane_b32 s22, v248, 25
	v_readlane_b32 s23, v248, 26
	s_add_u32 s20, s22, s20
	s_addc_u32 s21, s23, s21
	s_and_b64 s[22:23], s[4:5], exec
	s_cselect_b32 s19, s21, s29
	s_cselect_b32 s25, s20, s28
	s_ashr_i32 s17, s16, 31
	s_lshl_b64 s[22:23], s[16:17], 21
	v_readlane_b32 s34, v248, 29
	v_readlane_b32 s35, v248, 30
	s_add_u32 s22, s34, s22
	s_addc_u32 s23, s35, s23
	s_and_b64 s[34:35], s[4:5], exec
	s_cselect_b32 s17, s23, s31
	s_cselect_b32 s50, s22, s30
	s_add_u32 s28, s28, 0x100080
	s_addc_u32 s29, s29, 0
	s_add_u32 s51, s30, 0x100
	v_mov_b32_e32 v0, 0
	s_addc_u32 s52, s31, 0
	s_mov_b32 s53, -2
	s_waitcnt lgkmcnt(0)
	v_mov_b32_e32 v1, 0
	v_mov_b64_e32 v[2:3], 0
	v_mov_b64_e32 v[4:5], 0
	v_mov_b64_e32 v[6:7], 0
	v_mov_b64_e32 v[8:9], 0
	v_mov_b64_e32 v[10:11], 0
	v_mov_b64_e32 v[12:13], 0
	v_mov_b64_e32 v[14:15], 0
	v_mov_b64_e32 v[16:17], 0
	v_mov_b64_e32 v[18:19], 0
	v_mov_b64_e32 v[20:21], 0
	v_mov_b64_e32 v[22:23], 0
	v_mov_b64_e32 v[24:25], 0
	v_mov_b64_e32 v[26:27], 0
	v_mov_b64_e32 v[28:29], 0
	v_mov_b64_e32 v[30:31], 0
	v_mov_b64_e32 v[32:33], 0
	v_mov_b64_e32 v[34:35], 0
	v_mov_b64_e32 v[36:37], 0
	v_mov_b64_e32 v[38:39], 0
	v_mov_b64_e32 v[40:41], 0
	v_mov_b64_e32 v[42:43], 0
	v_mov_b64_e32 v[44:45], 0
	v_mov_b64_e32 v[46:47], 0
	v_mov_b64_e32 v[48:49], 0
	v_mov_b64_e32 v[50:51], 0
	v_mov_b64_e32 v[52:53], 0
	v_mov_b64_e32 v[54:55], 0
	v_mov_b64_e32 v[56:57], 0
	v_mov_b64_e32 v[58:59], 0
	v_mov_b64_e32 v[60:61], 0
	v_mov_b64_e32 v[62:63], 0
	v_mov_b64_e32 v[64:65], 0
	v_mov_b64_e32 v[66:67], 0
	v_mov_b64_e32 v[68:69], 0
	v_mov_b64_e32 v[70:71], 0
	v_mov_b64_e32 v[72:73], 0
	v_mov_b64_e32 v[74:75], 0
	v_mov_b64_e32 v[76:77], 0
	v_mov_b64_e32 v[78:79], 0
	v_mov_b64_e32 v[80:81], 0
	v_mov_b64_e32 v[82:83], 0
	v_mov_b64_e32 v[84:85], 0
	v_mov_b64_e32 v[86:87], 0
	v_mov_b64_e32 v[88:89], 0
	v_mov_b64_e32 v[90:91], 0
	v_mov_b64_e32 v[92:93], 0
	v_mov_b64_e32 v[94:95], 0
	v_mov_b64_e32 v[96:97], 0
	v_mov_b64_e32 v[98:99], 0
	v_mov_b64_e32 v[100:101], 0
	v_mov_b64_e32 v[102:103], 0
	v_mov_b64_e32 v[104:105], 0
	v_mov_b64_e32 v[106:107], 0
	v_mov_b64_e32 v[108:109], 0
	v_mov_b64_e32 v[110:111], 0
	v_mov_b64_e32 v[112:113], 0
	v_mov_b64_e32 v[114:115], 0
	v_mov_b64_e32 v[116:117], 0
	v_mov_b64_e32 v[118:119], 0
	v_mov_b64_e32 v[120:121], 0
	v_mov_b64_e32 v[122:123], 0
	v_mov_b64_e32 v[124:125], 0
	v_mov_b64_e32 v[126:127], 0
	s_nop 0
	s_nop 0
	s_nop 0
	s_nop 0
	s_nop 0
	s_nop 0
	s_nop 0
	s_nop 0
	s_nop 0
	s_nop 0

; template <class Epi, class Sched, bool ALIGN_EPI = false, bool SP2 = false>
; __device__ __forceinline__ void gemm_phase(PG8_LAS unsigned char* lds, const Gemm g, const Sched& S, const Epi& E, const int wave_) {
;     ...
;         const bool has_next = S.next(ui + 1, nxt);
;         const char* nA = has_next ? (const char*)g.A + (size_t)nxt.pm * tstep : cA; const char* nB = has_next ? (const char*)g.Bt + (size_t)nxt.pn * tstep : cB;
;     ...
; #pragma unroll
;         for (int a = 0; a < 2; ++a)
; #pragma unroll
;             for (int b = 0; b < 2; ++b)
; #pragma unroll
;                 for (int m = 0; m < 4; ++m)
; #pragma unroll
;                     for (int n = 0; n < 2; ++n) acc[a][b][m][n] = (f32x4){0.f, 0.f, 0.f, 0.f};
;         cur = nxt; cA = nA; cB = nB; ++ui;
.LBB0_494:
	s_ashr_i32 s29, s28, 31
	s_lshl_b64 s[30:31], s[28:29], 20
	s_add_u32 s30, s38, s30
	s_addc_u32 s31, s39, s31
	s_and_b64 s[34:35], s[0:1], exec
	s_cselect_b32 s5, s31, s37
	s_cselect_b32 s7, s30, s36
	s_ashr_i32 s27, s26, 31
	s_lshl_b64 s[34:35], s[26:27], 20
	v_readlane_b32 s42, v248, 31
	v_readlane_b32 s43, v248, 32
	s_add_u32 s34, s42, s34
	s_addc_u32 s35, s43, s35
	s_and_b64 s[42:43], s[0:1], exec
	s_cselect_b32 s27, s35, s41
	s_cselect_b32 s29, s34, s40
	s_add_u32 s36, s36, 0x80080
	s_addc_u32 s37, s37, 0
	s_add_u32 s61, s40, 0x100
	v_mov_b32_e32 v0, 0
	s_addc_u32 s62, s41, 0
	s_mov_b32 s63, -2
	v_mov_b32_e32 v1, 0
	v_mov_b64_e32 v[2:3], 0
	v_mov_b64_e32 v[4:5], 0
	v_mov_b64_e32 v[6:7], 0
	v_mov_b64_e32 v[8:9], 0
	v_mov_b64_e32 v[10:11], 0
	v_mov_b64_e32 v[12:13], 0
	v_mov_b64_e32 v[14:15], 0
	v_mov_b64_e32 v[16:17], 0
	v_mov_b64_e32 v[18:19], 0
	v_mov_b64_e32 v[20:21], 0
	v_mov_b64_e32 v[22:23], 0
	v_mov_b64_e32 v[24:25], 0
	v_mov_b64_e32 v[26:27], 0
	v_mov_b64_e32 v[28:29], 0
	v_mov_b64_e32 v[30:31], 0
	v_mov_b64_e32 v[32:33], 0
	v_mov_b64_e32 v[34:35], 0
	v_mov_b64_e32 v[36:37], 0
	v_mov_b64_e32 v[38:39], 0
	v_mov_b64_e32 v[40:41], 0
	v_mov_b64_e32 v[42:43], 0
	v_mov_b64_e32 v[44:45], 0
	v_mov_b64_e32 v[46:47], 0
	v_mov_b64_e32 v[48:49], 0
	v_mov_b64_e32 v[50:51], 0
	v_mov_b64_e32 v[52:53], 0
	v_mov_b64_e32 v[54:55], 0
	v_mov_b64_e32 v[56:57], 0
	v_mov_b64_e32 v[58:59], 0
	v_mov_b64_e32 v[60:61], 0
	v_mov_b64_e32 v[62:63], 0
	v_mov_b64_e32 v[64:65], 0
	v_mov_b64_e32 v[66:67], 0
	v_mov_b64_e32 v[68:69], 0
	v_mov_b64_e32 v[70:71], 0
	v_mov_b64_e32 v[72:73], 0
	v_mov_b64_e32 v[74:75], 0
	v_mov_b64_e32 v[76:77], 0
	v_mov_b64_e32 v[78:79], 0
	v_mov_b64_e32 v[80:81], 0
	v_mov_b64_e32 v[82:83], 0
	v_mov_b64_e32 v[84:85], 0
	v_mov_b64_e32 v[86:87], 0
	v_mov_b64_e32 v[88:89], 0
	v_mov_b64_e32 v[90:91], 0
	v_mov_b64_e32 v[92:93], 0
	v_mov_b64_e32 v[94:95], 0
	v_mov_b64_e32 v[96:97], 0
	v_mov_b64_e32 v[98:99], 0
	v_mov_b64_e32 v[100:101], 0
	v_mov_b64_e32 v[102:103], 0
	v_mov_b64_e32 v[104:105], 0
	v_mov_b64_e32 v[106:107], 0
	v_mov_b64_e32 v[108:109], 0
	v_mov_b64_e32 v[110:111], 0
	v_mov_b64_e32 v[112:113], 0
	v_mov_b64_e32 v[114:115], 0
	v_mov_b64_e32 v[116:117], 0
	v_mov_b64_e32 v[118:119], 0
	v_mov_b64_e32 v[120:121], 0
	v_mov_b64_e32 v[122:123], 0
	v_mov_b64_e32 v[124:125], 0
	v_mov_b64_e32 v[126:127], 0
	s_nop 0
	s_nop 0
	s_nop 0
	s_nop 0
	s_nop 0
	s_nop 0
	s_nop 0
	s_nop 0
	s_nop 0
	s_nop 0
	s_nop 0
	s_nop 0
	s_nop 0
	s_nop 0
	s_nop 0

; __device__ __forceinline__ int lane_id() { return (int)__builtin_amdgcn_mbcnt_hi(~0u, __builtin_amdgcn_mbcnt_lo(~0u, 0u)); }
; #define LAS __attribute__((address_space(3)))
; __device__ __forceinline__ s16x4 vtr(const LAS unsigned char* p) { return __builtin_bit_cast(s16x4, __builtin_amdgcn_ds_read_tr16_b64_v4i16((LAS s16x4*)p)); }
; __device__ __forceinline__ int crow(int r, int hi) { return (r & 3) + 8 * (r >> 2) + 4 * hi; }
; __device__ __forceinline__ void attn_unit(LAS unsigned char* lds, const int wid, int b, int h, int qb, const bf16_t* __restrict__ Q, const bf16_t* __restrict__ K,
;                                           const bf16_t* __restrict__ V, const bf16_t* __restrict__ ZS, bf16_t* __restrict__ OG) {
;     ...
;     { const LAS unsigned char* vbp = lds + 32768 + vprev * 16384;
; #pragma unroll
;       for (int c = 0; c < 4; ++c)
; #pragma unroll
;           for (int s = 0; s < 4; ++s) {
;               const s16x4 lo = vtr(vbp + 4096 * s + vbase[0] + vcq[c]);
;               const s16x4 hh = vtr(vbp + 4096 * s + vbase[1] + vcq[c]);
;               const bf16x8 vfr = (bf16x8){lo[0], lo[1], lo[2], lo[3], hh[0], hh[1], hh[2], hh[3]};
;               o[c] = __builtin_amdgcn_mfma_f32_32x32x16_bf16(pa[s], vfr, o[c], 0, 0, 0);
;           } }
;     {
;         int lane_e = lane_id(); asm volatile("" : "+v"(lane_e));
;         const int r32e = lane_e & 31, hie = lane_e >> 5, rowq = lane_e >> 3, c8 = (lane_e & 7) * 8;
;         LAS float* stg = (LAS float*)(lds + 81920 + wid * 8192);
;         const size_t gbase = (tok0 + qw0) * DM + h * HD + c8;
;         u32x4 zv[2][4];
; #pragma unroll
;         for (int ps = 0; ps < 2; ++ps)
; #pragma unroll
;             for (int j = 0; j < 4; ++j) zv[ps][j] = *(const u32x4*)(ZS + gbase + (size_t)(8 * j + rowq) * DM + 64 * ps);
; #pragma unroll
;         for (int ps = 0; ps < 2; ++ps) {
; #pragma unroll
;             for (int r = 0; r < 16; ++r) {
;                 stg[crow(r, hie) * 64 + r32e] = o[2 * ps][r];
;                 stg[crow(r, hie) * 64 + 32 + r32e] = o[2 * ps + 1][r];
;             }
.LBB0_611:
	s_lshl_b32 s4, s71, 14
	s_add_i32 s4, s4, 0
	v_add_u32_e32 v112, s4, v188
	v_add_u32_e32 v113, s4, v189
	v_add_u32_e32 v86, v112, v190
	v_add_u32_e32 v94, v113, v190
	ds_read_b64_tr_b16 v[82:83], v94 offset:34816
	ds_read_b64_tr_b16 v[80:81], v86 offset:32768
	ds_read_b64_tr_b16 v[84:85], v86 offset:36864
	ds_read_b64_tr_b16 v[88:89], v86 offset:40960
	ds_read_b64_tr_b16 v[92:93], v86 offset:45056
	ds_read_b64_tr_b16 v[86:87], v94 offset:38912
	ds_read_b64_tr_b16 v[90:91], v94 offset:43008
	ds_read_b64_tr_b16 v[94:95], v94 offset:47104
	s_waitcnt lgkmcnt(6)
	v_mfma_f32_32x32x16_bf16 v[32:47], v[64:67], v[80:83], v[32:47]
	v_add_u32_e32 v82, v112, v191
	v_add_u32_e32 v98, v113, v191
	v_add_u32_e32 v102, v112, v192
	v_add_u32_e32 v110, v113, v192
	v_mov_b32_e32 v144, v195
	s_add_u32 s4, s50, s64
	s_addc_u32 s5, s51, 0
	s_waitcnt lgkmcnt(2)
	v_mfma_f32_32x32x16_bf16 v[32:47], v[68:71], v[84:87], v[32:47]
	s_lshl_b64 s[4:5], s[4:5], 11
	s_xor_b32 s7, s63, 0xf00
	s_add_i32 s63, s7, s54
	s_lshl_b32 s42, s62, 1
	s_mov_b32 m0, s55
	s_mov_b32 s64, 1
	s_mov_b32 s6, 2
	s_waitcnt lgkmcnt(1)
	v_mfma_f32_32x32x16_bf16 v[32:47], v[72:75], v[88:91], v[32:47]
	ds_read_b64_tr_b16 v[80:81], v82 offset:32768
	ds_read_b64_tr_b16 v[84:85], v82 offset:36864
	ds_read_b64_tr_b16 v[88:89], v82 offset:40960
	ds_read_b64_tr_b16 v[96:97], v82 offset:45056
	s_or_b32 s65, s63, 31
	s_add_i32 s66, s7, 0xff
	s_mov_b32 s67, 0
	s_mov_b32 s71, 0
	s_waitcnt lgkmcnt(4)
	v_mfma_f32_32x32x16_bf16 v[32:47], v[76:79], v[92:95], v[32:47]
	ds_read_b64_tr_b16 v[82:83], v98 offset:34816
	ds_read_b64_tr_b16 v[86:87], v98 offset:38912
	ds_read_b64_tr_b16 v[90:91], v98 offset:43008
	ds_read_b64_tr_b16 v[98:99], v98 offset:47104
	ds_read_b64_tr_b16 v[92:93], v102 offset:32768
	ds_read_b64_tr_b16 v[100:101], v102 offset:36864
	ds_read_b64_tr_b16 v[104:105], v102 offset:40960
	ds_read_b64_tr_b16 v[108:109], v102 offset:45056
	ds_read_b64_tr_b16 v[94:95], v110 offset:34816
	ds_read_b64_tr_b16 v[102:103], v110 offset:38912
	ds_read_b64_tr_b16 v[106:107], v110 offset:43008
	ds_read_b64_tr_b16 v[110:111], v110 offset:47104
	s_waitcnt lgkmcnt(11)
	v_mfma_f32_32x32x16_bf16 v[48:63], v[64:67], v[80:83], v[48:63]
	v_add_u32_e32 v80, v112, v193
	v_add_u32_e32 v81, v113, v193
	ds_read_b64_tr_b16 v[112:113], v80 offset:32768
	ds_read_b64_tr_b16 v[116:117], v80 offset:36864
	ds_read_b64_tr_b16 v[120:121], v80 offset:40960
	ds_read_b64_tr_b16 v[124:125], v80 offset:45056
	ds_read_b64_tr_b16 v[114:115], v81 offset:34816
	ds_read_b64_tr_b16 v[118:119], v81 offset:38912
	ds_read_b64_tr_b16 v[122:123], v81 offset:43008
	ds_read_b64_tr_b16 v[126:127], v81 offset:47104
	v_mov_b32_e32 v81, s5
	v_lshlrev_b32_e32 v80, 3, v144
	s_waitcnt lgkmcnt(14)
	v_mfma_f32_32x32x16_bf16 v[48:63], v[68:71], v[84:87], v[48:63]
	v_and_b32_e32 v149, 56, v80
	v_or_b32_e32 v80, s4, v149
	v_ashrrev_i32_e32 v132, 3, v144
	v_or_b32_e32 v80, s62, v80
	v_lshlrev_b64 v[134:135], 1, v[80:81]
	v_ashrrev_i32_e32 v133, 31, v132
	v_lshl_add_u64 v[80:81], s[46:47], 0, v[134:135]
	v_lshlrev_b64 v[136:137], 12, v[132:133]
	v_lshl_add_u64 v[82:83], v[80:81], 0, v[136:137]
	v_mfma_f32_32x32x16_bf16 v[48:63], v[72:75], v[88:91], v[48:63]
	global_load_dwordx4 v[88:91], v[82:83], off
	v_add_u32_e32 v138, 8, v132
	v_ashrrev_i32_e32 v139, 31, v138
	v_lshlrev_b64 v[140:141], 12, v[138:139]
	v_lshl_add_u64 v[84:85], v[80:81], 0, v[140:141]
	v_add_u32_e32 v142, 16, v132
	v_add_u32_e32 v160, 24, v132
	s_waitcnt lgkmcnt(11)
	v_mfma_f32_32x32x16_bf16 v[0:15], v[64:67], v[92:95], v[0:15]
	global_load_dwordx4 v[92:95], v[84:85], off
	v_ashrrev_i32_e32 v143, 31, v142
	v_ashrrev_i32_e32 v161, 31, v160
	v_lshlrev_b64 v[158:159], 12, v[142:143]
	v_lshlrev_b64 v[162:163], 12, v[160:161]
	v_lshl_add_u64 v[86:87], v[80:81], 0, v[158:159]
	v_lshl_add_u64 v[80:81], v[80:81], 0, v[162:163]
	s_waitcnt lgkmcnt(10)
	v_mfma_f32_32x32x16_bf16 v[0:15], v[68:71], v[100:103], v[0:15]
	v_and_b32_e32 v133, 31, v144
	v_lshlrev_b32_e32 v133, 2, v133
	v_readlane_b32 s4, v248, 25
	v_readlane_b32 s5, v248, 26
	v_mov_b32_e32 v143, 0
	v_mov_b32_e32 v139, 0
	v_mfma_f32_32x32x16_bf16 v[48:63], v[76:79], v[96:99], v[48:63]
	global_load_dwordx4 v[96:99], v[82:83], off offset:128
	s_waitcnt lgkmcnt(9)
	v_mfma_f32_32x32x16_bf16 v[0:15], v[72:75], v[104:107], v[0:15]
	global_load_dwordx4 v[100:103], v[84:85], off offset:128
	global_load_dwordx4 v[104:107], v[86:87], off
	s_nop 0
	global_load_dwordx4 v[84:87], v[86:87], off offset:128
	s_nop 0
	global_load_dwordx4 v[128:131], v[80:81], off
	s_nop 0
	global_load_dwordx4 v[80:83], v[80:81], off offset:128
	s_waitcnt lgkmcnt(8)
	v_mfma_f32_32x32x16_bf16 v[0:15], v[76:79], v[108:111], v[0:15]
	v_lshlrev_b32_e32 v110, 5, v144
	v_and_b32_e32 v110, 0xfffffc00, v110
	v_add3_u32 v110, s56, v133, v110
	ds_write2_b32 v110, v32, v48 offset1:32
	ds_write2_b32 v110, v33, v49 offset0:64 offset1:96
	ds_write2_b32 v110, v34, v50 offset0:128 offset1:160
	ds_write2_b32 v110, v35, v51 offset0:192 offset1:224
	v_add_u32_e32 v48, 0x800, v110
	v_add_u32_e32 v49, 0x1000, v110
	v_add_u32_e32 v50, 0x1800, v110
	v_lshl_add_u32 v108, v149, 2, s56
	ds_write2_b32 v48, v36, v52 offset1:32
	ds_write2_b32 v48, v37, v53 offset0:64 offset1:96
	ds_write2_b32 v48, v38, v54 offset0:128 offset1:160
	ds_write2_b32 v48, v39, v55 offset0:192 offset1:224
	ds_write2_b32 v49, v40, v56 offset1:32
	ds_write2_b32 v49, v41, v57 offset0:64 offset1:96
	ds_write2_b32 v49, v42, v58 offset0:128 offset1:160
	ds_write2_b32 v49, v43, v59 offset0:192 offset1:224
	ds_write2_b32 v50, v44, v60 offset1:32
	ds_write2_b32 v50, v45, v61 offset0:64 offset1:96
	ds_write2_b32 v50, v46, v62 offset0:128 offset1:160
	ds_write2_b32 v50, v47, v63 offset0:192 offset1:224
	v_lshl_add_u32 v109, v132, 8, v108
	s_waitcnt lgkmcnt(0)
; #define LAS __attribute__((address_space(3)))
; __device__ __forceinline__ unsigned pk_bf16(float lo, float hi) { return pg8::cvt_pk_bf16(lo, hi); }
; __device__ __forceinline__ float bf_lo(unsigned w) { return __uint_as_float(w << 16); }
; __device__ __forceinline__ float bf_hi(unsigned w) { return __uint_as_float(w & 0xffff0000u); }
; __device__ __forceinline__ int crow(int r, int hi) { return (r & 3) + 8 * (r >> 2) + 4 * hi; }
; __device__ __forceinline__ void attn_unit(LAS unsigned char* lds, const int wid, int b, int h, int qb, const bf16_t* __restrict__ Q, const bf16_t* __restrict__ K,
;                                           const bf16_t* __restrict__ V, const bf16_t* __restrict__ ZS, bf16_t* __restrict__ OG) {
;     ...
;         for (int ps = 0; ps < 2; ++ps) {
; #pragma unroll
;             for (int r = 0; r < 16; ++r) {
;                 stg[crow(r, hie) * 64 + r32e] = o[2 * ps][r];
;                 stg[crow(r, hie) * 64 + 32 + r32e] = o[2 * ps + 1][r];
;             }
;             asm volatile("s_waitcnt lgkmcnt(0)" ::: "memory");
; #pragma unroll
;             for (int j = 0; j < 4; ++j) {
;                 const f32x4 oa = *(const LAS f32x4*)(stg + (8 * j + rowq) * 64 + c8), ob = *(const LAS f32x4*)(stg + (8 * j + rowq) * 64 + c8 + 4);
;                 const u32x4 z = zv[ps][j];
;                 u32x4 w; w.x = pk_bf16(oa[0] * bf_lo(z.x), oa[1] * bf_hi(z.x)); w.y = pk_bf16(oa[2] * bf_lo(z.y), oa[3] * bf_hi(z.y));
;                 w.z = pk_bf16(ob[0] * bf_lo(z.z), ob[1] * bf_hi(z.z)); w.w = pk_bf16(ob[2] * bf_lo(z.w), ob[3] * bf_hi(z.w));
;                 *(u32x4*)(OG + gbase + (size_t)(8 * j + rowq) * DM + 64 * ps) = w;
;             }
;             asm volatile("s_waitcnt lgkmcnt(0)" ::: "memory");
;         }
	ds_read_b128 v[32:35], v109
	ds_read_b128 v[36:39], v109 offset:16
	v_lshl_add_u32 v51, v138, 8, v108
	v_lshl_add_u64 v[40:41], s[4:5], 0, v[134:135]
	s_waitcnt lgkmcnt(14)
	v_mfma_f32_32x32x16_bf16 v[16:31], v[64:67], v[112:115], v[16:31]
	v_lshl_add_u32 v52, v142, 8, v108
	v_lshl_add_u32 v53, v160, 8, v108
	v_or_b32_e32 v144, s63, v178
	v_mov_b32_e32 v149, v145
	s_add_i32 s4, s7, 0x100
	s_lshr_b32 s8, s4, 6
	v_mov_b32_e32 v142, 0
	v_mfma_f32_32x32x16_bf16 v[16:31], v[68:71], v[116:119], v[16:31]
	v_mov_b32_e32 v138, 0
	v_mov_b32_e32 v132, 0
	v_mov_b32_e32 v133, 0
	v_mov_b32_e32 v134, 0
	v_mov_b32_e32 v135, 0
	s_waitcnt vmcnt(7)
	v_lshlrev_b32_e32 v42, 16, v88
	s_waitcnt lgkmcnt(1)
	v_mul_f32_e32 v32, v32, v42
	v_and_b32_e32 v42, 0xffff0000, v88
	v_mul_f32_e32 v33, v33, v42
	v_cvt_pk_bf16_f32 v32, v32, v33
	v_lshlrev_b32_e32 v33, 16, v89
	v_mul_f32_e32 v33, v34, v33
	v_and_b32_e32 v34, 0xffff0000, v89
	v_mul_f32_e32 v34, v35, v34
	v_cvt_pk_bf16_f32 v33, v33, v34
	v_lshlrev_b32_e32 v34, 16, v90
	v_and_b32_e32 v35, 0xffff0000, v90
	s_waitcnt lgkmcnt(0)
	v_mul_f32_e32 v34, v36, v34
	v_mul_f32_e32 v35, v37, v35
	v_cvt_pk_bf16_f32 v34, v34, v35
	v_lshlrev_b32_e32 v35, 16, v91
	v_and_b32_e32 v36, 0xffff0000, v91
	v_mul_f32_e32 v35, v38, v35
	v_mul_f32_e32 v36, v39, v36
	v_cvt_pk_bf16_f32 v35, v35, v36
	ds_read_b128 v[36:39], v51
	v_lshl_add_u64 v[42:43], v[40:41], 0, v[136:137]
	s_waitcnt vmcnt(6)
	v_lshlrev_b32_e32 v44, 16, v92
	global_store_dwordx4 v[42:43], v[32:35], off sc1
	ds_read_b128 v[32:35], v51 offset:16
	s_waitcnt lgkmcnt(1)
	v_mul_f32_e32 v36, v36, v44
	v_and_b32_e32 v44, 0xffff0000, v92
	v_mul_f32_e32 v37, v37, v44
	v_cvt_pk_bf16_f32 v36, v36, v37
	v_lshlrev_b32_e32 v37, 16, v93
	v_mul_f32_e32 v37, v38, v37
	v_and_b32_e32 v38, 0xffff0000, v93
	v_mul_f32_e32 v38, v39, v38
	v_cvt_pk_bf16_f32 v37, v37, v38
	v_lshlrev_b32_e32 v38, 16, v94
	s_waitcnt lgkmcnt(0)
	v_mul_f32_e32 v32, v32, v38
	v_and_b32_e32 v38, 0xffff0000, v94
	v_mul_f32_e32 v33, v33, v38
	v_cvt_pk_bf16_f32 v38, v32, v33
	v_lshlrev_b32_e32 v32, 16, v95
	v_and_b32_e32 v33, 0xffff0000, v95
	v_mul_f32_e32 v32, v34, v32
	v_mul_f32_e32 v33, v35, v33
	v_cvt_pk_bf16_f32 v39, v32, v33
	ds_read_b128 v[32:35], v52
	v_lshl_add_u64 v[44:45], v[40:41], 0, v[140:141]
	s_waitcnt vmcnt(4)
	v_lshlrev_b32_e32 v46, 16, v104
	global_store_dwordx4 v[44:45], v[36:39], off sc1
	ds_read_b128 v[36:39], v52 offset:16
	s_waitcnt lgkmcnt(1)
	v_mul_f32_e32 v32, v32, v46
	v_and_b32_e32 v46, 0xffff0000, v104
	v_mul_f32_e32 v33, v33, v46
	v_cvt_pk_bf16_f32 v32, v32, v33
	v_lshlrev_b32_e32 v33, 16, v105
	v_mul_f32_e32 v33, v34, v33
	v_and_b32_e32 v34, 0xffff0000, v105
	v_mul_f32_e32 v34, v35, v34
	v_cvt_pk_bf16_f32 v33, v33, v34
	v_lshlrev_b32_e32 v34, 16, v106
	v_and_b32_e32 v35, 0xffff0000, v106
	s_waitcnt lgkmcnt(0)
	v_mul_f32_e32 v34, v36, v34
	v_mul_f32_e32 v35, v37, v35
	v_cvt_pk_bf16_f32 v34, v34, v35
	v_lshlrev_b32_e32 v35, 16, v107
	v_and_b32_e32 v36, 0xffff0000, v107
	v_mul_f32_e32 v35, v38, v35
	v_mul_f32_e32 v36, v39, v36
	v_cvt_pk_bf16_f32 v35, v35, v36
	ds_read_b128 v[36:39], v53
	v_mfma_f32_32x32x16_bf16 v[16:31], v[72:75], v[120:123], v[16:31]
	v_lshl_add_u64 v[46:47], v[40:41], 0, v[158:159]
	s_waitcnt vmcnt(3)
	v_lshlrev_b32_e32 v54, 16, v128
	global_store_dwordx4 v[46:47], v[32:35], off sc1
	ds_read_b128 v[32:35], v53 offset:16
	s_waitcnt lgkmcnt(1)
	v_mul_f32_e32 v36, v36, v54
	v_and_b32_e32 v54, 0xffff0000, v128
	v_mul_f32_e32 v37, v37, v54
	v_cvt_pk_bf16_f32 v36, v36, v37
	v_lshlrev_b32_e32 v37, 16, v129
	v_mul_f32_e32 v37, v38, v37
	v_and_b32_e32 v38, 0xffff0000, v129
	v_mfma_f32_32x32x16_bf16 v[16:31], v[76:79], v[124:127], v[16:31]
	v_mul_f32_e32 v38, v39, v38
	v_cvt_pk_bf16_f32 v37, v37, v38
	v_lshlrev_b32_e32 v38, 16, v130
	s_waitcnt lgkmcnt(0)
	v_mul_f32_e32 v32, v32, v38
	v_and_b32_e32 v38, 0xffff0000, v130
	v_mul_f32_e32 v33, v33, v38
	v_cvt_pk_bf16_f32 v38, v32, v33
	v_lshlrev_b32_e32 v32, 16, v131
	v_and_b32_e32 v33, 0xffff0000, v131
	v_mul_f32_e32 v32, v34, v32
	v_mul_f32_e32 v33, v35, v33
	v_cvt_pk_bf16_f32 v39, v32, v33
	v_lshl_add_u64 v[32:33], v[40:41], 0, v[162:163]
	global_store_dwordx4 v[32:33], v[36:39], off sc1
	s_waitcnt lgkmcnt(0)
	ds_write2_b32 v110, v0, v16 offset1:32
	ds_write2_b32 v110, v1, v17 offset0:64 offset1:96
	ds_write2_b32 v110, v2, v18 offset0:128 offset1:160
	ds_write2_b32 v110, v3, v19 offset0:192 offset1:224
	ds_write2_b32 v48, v4, v20 offset1:32
	ds_write2_b32 v48, v5, v21 offset0:64 offset1:96
	ds_write2_b32 v48, v6, v22 offset0:128 offset1:160
	ds_write2_b32 v48, v7, v23 offset0:192 offset1:224
	ds_write2_b32 v49, v8, v24 offset1:32
	ds_write2_b32 v49, v9, v25 offset0:64 offset1:96
	ds_write2_b32 v49, v10, v26 offset0:128 offset1:160
	ds_write2_b32 v49, v11, v27 offset0:192 offset1:224
	ds_write2_b32 v50, v12, v28 offset1:32
	ds_write2_b32 v50, v13, v29 offset0:64 offset1:96
	ds_write2_b32 v50, v14, v30 offset0:128 offset1:160
	ds_write2_b32 v50, v15, v31 offset0:192 offset1:224
	s_waitcnt lgkmcnt(0)
	ds_read_b128 v[0:3], v109
	ds_read_b128 v[4:7], v109 offset:16
	v_lshlrev_b32_e32 v8, 16, v96
	v_mov_b32_e32 v34, v145
	v_mov_b32_e32 v35, v145
	s_waitcnt lgkmcnt(1)
	v_mul_f32_e32 v0, v0, v8
	v_and_b32_e32 v8, 0xffff0000, v96
	v_mul_f32_e32 v1, v1, v8
	v_cvt_pk_bf16_f32 v0, v0, v1
	v_lshlrev_b32_e32 v1, 16, v97
	v_mul_f32_e32 v1, v2, v1
	v_and_b32_e32 v2, 0xffff0000, v97
	v_mul_f32_e32 v2, v3, v2
	v_cvt_pk_bf16_f32 v1, v1, v2
	v_lshlrev_b32_e32 v2, 16, v98
	v_and_b32_e32 v3, 0xffff0000, v98
	s_waitcnt lgkmcnt(0)
; __device__ __forceinline__ void attn_unit(LAS unsigned char* lds, const int wid, int b, int h, int qb, const bf16_t* __restrict__ Q, const bf16_t* __restrict__ K,
;                                           const bf16_t* __restrict__ V, const bf16_t* __restrict__ ZS, bf16_t* __restrict__ OG) {
;     ...
;     const int q0 = qb * 256, qw0 = q0 + 32 * wid, qabs = qw0 + r32;
;     bf16x8 qf[8];
;     { const bf16_t* qp = Q + (tok0 + qabs) * DM + h * HD + 8 * hi;
; #pragma unroll
;       for (int d0 = 0; d0 < 8; ++d0) qf[d0] = *(const bf16x8*)(qp + 16 * d0); }
;     f32x16 o[4];
; #pragma unroll
;     for (int c = 0; c < 4; ++c)
; #pragma unroll
;         for (int r = 0; r < 16; ++r) o[c][r] = 0.f;
;     bf16x8 pa[4];
; #pragma unroll
;     for (int s = 0; s < 4; ++s) pa[s] = (bf16x8){0, 0, 0, 0, 0, 0, 0, 0};
;     float carry = 0.f;
;     const int NT = (q0 + 256) / 64;
;     const int srow = tid >> 4, sch = (tid & 15) ^ (((srow & 3) << 2) | ((srow >> 2) & 3));
;     const bf16_t* kg = K + (tok0 + srow) * DM + h * HD + sch * 8;
;     const bf16_t* vg = V + (tok0 + srow) * DM + h * HD + sch * 8;
;     LAS unsigned char* ldsw = lds + wid * 1024;
;     ...
;     ATT_STAGE(NT - 1, 0, 32768);
;     ...
;             for (int j = 0; j < 4; ++j) zv[ps][j] = *(const u32x4*)(ZS + gbase + (size_t)(8 * j + rowq) * DM + 64 * ps);
; #pragma unroll
;         for (int ps = 0; ps < 2; ++ps) {
; #pragma unroll
;             for (int r = 0; r < 16; ++r) {
;                 stg[crow(r, hie) * 64 + r32e] = o[2 * ps][r];
;                 stg[crow(r, hie) * 64 + 32 + r32e] = o[2 * ps + 1][r];
;             }
;             asm volatile("s_waitcnt lgkmcnt(0)" ::: "memory");
; #pragma unroll
;             for (int j = 0; j < 4; ++j) {
;                 const f32x4 oa = *(const LAS f32x4*)(stg + (8 * j + rowq) * 64 + c8), ob = *(const LAS f32x4*)(stg + (8 * j + rowq) * 64 + c8 + 4);
;                 const u32x4 z = zv[ps][j];
;                 u32x4 w; w.x = pk_bf16(oa[0] * bf_lo(z.x), oa[1] * bf_hi(z.x)); w.y = pk_bf16(oa[2] * bf_lo(z.y), oa[3] * bf_hi(z.y));
;                 w.z = pk_bf16(ob[0] * bf_lo(z.z), ob[1] * bf_hi(z.z)); w.w = pk_bf16(ob[2] * bf_lo(z.w), ob[3] * bf_hi(z.w));
;                 *(u32x4*)(OG + gbase + (size_t)(8 * j + rowq) * DM + 64 * ps) = w;
;             }
;             asm volatile("s_waitcnt lgkmcnt(0)" ::: "memory");
;         }
;     }
;     __syncthreads();
	v_mul_f32_e32 v2, v4, v2
	v_mul_f32_e32 v3, v5, v3
	v_cvt_pk_bf16_f32 v2, v2, v3
	v_lshlrev_b32_e32 v3, 16, v99
	v_and_b32_e32 v4, 0xffff0000, v99
	v_mul_f32_e32 v3, v6, v3
	v_mul_f32_e32 v4, v7, v4
	v_cvt_pk_bf16_f32 v3, v3, v4
	ds_read_b128 v[4:7], v51
	v_lshlrev_b32_e32 v8, 16, v100
	global_store_dwordx4 v[42:43], v[0:3], off offset:128 sc1
	ds_read_b128 v[0:3], v51 offset:16
	v_mov_b32_e32 v36, v145
	s_waitcnt lgkmcnt(1)
	v_mul_f32_e32 v4, v4, v8
	v_and_b32_e32 v8, 0xffff0000, v100
	v_mul_f32_e32 v5, v5, v8
	v_cvt_pk_bf16_f32 v4, v4, v5
	v_lshlrev_b32_e32 v5, 16, v101
	v_mul_f32_e32 v5, v6, v5
	v_and_b32_e32 v6, 0xffff0000, v101
	v_mul_f32_e32 v6, v7, v6
	v_cvt_pk_bf16_f32 v5, v5, v6
	v_lshlrev_b32_e32 v6, 16, v102
	s_waitcnt lgkmcnt(0)
	v_mul_f32_e32 v0, v0, v6
	v_and_b32_e32 v6, 0xffff0000, v102
	v_mul_f32_e32 v1, v1, v6
	v_cvt_pk_bf16_f32 v6, v0, v1
	v_lshlrev_b32_e32 v0, 16, v103
	v_and_b32_e32 v1, 0xffff0000, v103
	v_mul_f32_e32 v0, v2, v0
	v_mul_f32_e32 v1, v3, v1
	v_cvt_pk_bf16_f32 v7, v0, v1
	ds_read_b128 v[0:3], v52
	v_lshlrev_b32_e32 v8, 16, v84
	global_store_dwordx4 v[44:45], v[4:7], off offset:128 sc1
	ds_read_b128 v[4:7], v52 offset:16
	v_mov_b32_e32 v37, v145
	s_waitcnt lgkmcnt(1)
	v_mul_f32_e32 v0, v0, v8
	v_and_b32_e32 v8, 0xffff0000, v84
	v_mul_f32_e32 v1, v1, v8
	v_cvt_pk_bf16_f32 v0, v0, v1
	v_lshlrev_b32_e32 v1, 16, v85
	v_mul_f32_e32 v1, v2, v1
	v_and_b32_e32 v2, 0xffff0000, v85
	v_mul_f32_e32 v2, v3, v2
	v_cvt_pk_bf16_f32 v1, v1, v2
	v_lshlrev_b32_e32 v2, 16, v86
	v_and_b32_e32 v3, 0xffff0000, v86
	s_waitcnt lgkmcnt(0)
	v_mul_f32_e32 v2, v4, v2
	v_mul_f32_e32 v3, v5, v3
	v_cvt_pk_bf16_f32 v2, v2, v3
	v_lshlrev_b32_e32 v3, 16, v87
	v_and_b32_e32 v4, 0xffff0000, v87
	v_mul_f32_e32 v3, v6, v3
	v_mul_f32_e32 v4, v7, v4
	v_cvt_pk_bf16_f32 v3, v3, v4
	ds_read_b128 v[4:7], v53
	s_waitcnt vmcnt(6)
	v_lshlrev_b32_e32 v8, 16, v80
	global_store_dwordx4 v[46:47], v[0:3], off offset:128 sc1
	ds_read_b128 v[0:3], v53 offset:16
	v_mov_b32_e32 v46, v145
	s_waitcnt lgkmcnt(1)
	v_mul_f32_e32 v4, v4, v8
	v_and_b32_e32 v8, 0xffff0000, v80
	v_mul_f32_e32 v5, v5, v8
	v_cvt_pk_bf16_f32 v4, v4, v5
	v_lshlrev_b32_e32 v5, 16, v81
	v_mul_f32_e32 v5, v6, v5
	v_and_b32_e32 v6, 0xffff0000, v81
	v_mul_f32_e32 v6, v7, v6
	v_cvt_pk_bf16_f32 v5, v5, v6
	v_lshlrev_b32_e32 v6, 16, v82
	s_waitcnt lgkmcnt(0)
	v_mul_f32_e32 v0, v0, v6
	v_and_b32_e32 v6, 0xffff0000, v82
	v_mul_f32_e32 v1, v1, v6
	v_cvt_pk_bf16_f32 v6, v0, v1
	v_lshlrev_b32_e32 v0, 16, v83
	v_and_b32_e32 v1, 0xffff0000, v83
	v_mul_f32_e32 v0, v2, v0
	v_mul_f32_e32 v1, v3, v1
	v_cvt_pk_bf16_f32 v7, v0, v1
	v_lshl_add_u64 v[0:1], s[50:51], 0, v[144:145]
	v_lshlrev_b64 v[0:1], 12, v[0:1]
	v_lshl_add_u64 v[0:1], s[92:93], 0, v[0:1]
	v_lshl_add_u64 v[0:1], v[0:1], 0, s[42:43]
	global_store_dwordx4 v[32:33], v[4:7], off offset:128 sc1
	v_lshl_add_u64 v[0:1], v[0:1], 0, v[148:149]
	s_waitcnt lgkmcnt(0)
	s_barrier
	global_load_dwordx4 v[96:99], v[0:1], off
	global_load_dwordx4 v[100:103], v[0:1], off offset:32
	global_load_dwordx4 v[104:107], v[0:1], off offset:64
	global_load_dwordx4 v[108:111], v[0:1], off offset:96
	global_load_dwordx4 v[112:115], v[0:1], off offset:128
	global_load_dwordx4 v[116:119], v[0:1], off offset:160
	global_load_dwordx4 v[120:123], v[0:1], off offset:192
	global_load_dwordx4 v[124:127], v[0:1], off offset:224
	s_add_i32 s42, s8, -1
	s_lshl_b64 s[4:5], s[42:43], 18
	v_lshl_add_u64 v[0:1], v[154:155], 0, s[4:5]
	global_load_lds_dwordx4 v[0:1], off
	v_lshl_add_u64 v[0:1], v[0:1], 0, s[48:49]
	s_mov_b32 m0, s59
	v_mov_b32_e32 v32, v145
	global_load_lds_dwordx4 v[0:1], off
	v_lshl_add_u64 v[0:1], v[156:157], 0, s[4:5]
	s_mov_b32 m0, s60
	v_mov_b32_e32 v33, v145
	global_load_lds_dwordx4 v[0:1], off
	v_lshl_add_u64 v[0:1], v[0:1], 0, s[48:49]
	s_mov_b32 m0, s61
	v_mov_b32_e32 v47, v145
	global_load_lds_dwordx4 v[0:1], off
	s_waitcnt vmcnt(0)
	v_mov_b32_e32 v38, v145
	v_mov_b32_e32 v39, v145
	v_mov_b32_e32 v40, v145
	v_mov_b32_e32 v41, v145
	v_mov_b32_e32 v42, v145
	v_mov_b32_e32 v43, v145
	v_mov_b32_e32 v44, v145
	v_mov_b32_e32 v45, v145
	v_mov_b64_e32 v[62:63], v[46:47]
	v_mov_b64_e32 v[0:1], v[32:33]
	v_mov_b64_e32 v[16:17], v[32:33]
	s_add_i32 s42, s8, -2
	v_mov_b32_e32 v158, 0
	s_mov_b64 s[4:5], 0
	v_mov_b32_e32 v140, 0
	v_mov_b32_e32 v141, 0
	v_mov_b32_e32 v136, 0
	v_mov_b32_e32 v137, 0
	v_mov_b32_e32 v128, 0
	v_mov_b32_e32 v129, 0
	v_mov_b32_e32 v130, 0
	v_mov_b32_e32 v131, 0
	v_mov_b64_e32 v[60:61], v[44:45]
	v_mov_b64_e32 v[58:59], v[42:43]
	v_mov_b64_e32 v[56:57], v[40:41]
	v_mov_b64_e32 v[54:55], v[38:39]
	v_mov_b64_e32 v[52:53], v[36:37]
	v_mov_b64_e32 v[50:51], v[34:35]
	v_mov_b64_e32 v[48:49], v[32:33]
	v_mov_b64_e32 v[2:3], v[34:35]
	v_mov_b64_e32 v[4:5], v[36:37]
	v_mov_b64_e32 v[6:7], v[38:39]
	v_mov_b64_e32 v[8:9], v[40:41]
	v_mov_b64_e32 v[10:11], v[42:43]
	v_mov_b64_e32 v[12:13], v[44:45]
	v_mov_b64_e32 v[14:15], v[46:47]
	v_mov_b64_e32 v[18:19], v[34:35]
	v_mov_b64_e32 v[20:21], v[36:37]
	v_mov_b64_e32 v[22:23], v[38:39]
	v_mov_b64_e32 v[24:25], v[40:41]
	v_mov_b64_e32 v[26:27], v[42:43]
	v_mov_b64_e32 v[28:29], v[44:45]
	v_mov_b64_e32 v[30:31], v[46:47]
	s_waitcnt vmcnt(0) lgkmcnt(0)
	s_barrier
	s_mov_b32 s72, s6
	s_cmp_lg_u32 s42, -1
	s_mov_b64 s[6:7], -1
	s_cbranch_scc0 .LBB0_613
	s_nop 0
	s_nop 0
	s_nop 0
	s_nop 0
	s_nop 0
	s_nop 0
	s_nop 0
	s_nop 0
	s_nop 0
	s_nop 0
	s_nop 0

; template <class Epi, class Sched, bool ALIGN_EPI = false, bool SP2 = false>
; __device__ __forceinline__ void gemm_phase(PG8_LAS unsigned char* lds, const Gemm g, const Sched& S, const Epi& E, const int wave_) {
;     ...
;         const bool has_next = S.next(ui + 1, nxt);
;         const char* nA = has_next ? (const char*)g.A + (size_t)nxt.pm * tstep : cA; const char* nB = has_next ? (const char*)g.Bt + (size_t)nxt.pn * tstep : cB;
;     ...
; #pragma unroll
;         for (int a = 0; a < 2; ++a)
; #pragma unroll
;             for (int b = 0; b < 2; ++b)
; #pragma unroll
;                 for (int m = 0; m < 4; ++m)
; #pragma unroll
;                     for (int n = 0; n < 2; ++n) acc[a][b][m][n] = (f32x4){0.f, 0.f, 0.f, 0.f};
;         cur = nxt; cA = nA; cB = nB; ++ui;
.LBB0_699:
	s_ashr_i32 s23, s22, 31
	s_lshl_b64 s[24:25], s[22:23], 20
	v_readlane_b32 s26, v248, 25
	v_readlane_b32 s27, v248, 26
	s_add_u32 s24, s26, s24
	s_addc_u32 s25, s27, s25
	s_and_b64 s[26:27], s[6:7], exec
	s_cselect_b32 s23, s25, s35
	s_cselect_b32 s29, s24, s34
	s_ashr_i32 s21, s20, 31
	s_lshl_b64 s[26:27], s[20:21], 20
	s_add_u32 s26, s62, s26
	s_addc_u32 s27, s63, s27
	s_and_b64 s[40:41], s[6:7], exec
	s_cselect_b32 s21, s27, s37
	s_cselect_b32 s31, s26, s36
	s_add_u32 s34, s34, 0x80080
	s_addc_u32 s35, s35, 0
	s_add_u32 s56, s36, 0x100
	v_mov_b32_e32 v0, 0
	s_addc_u32 s57, s37, 0
	s_mov_b32 s58, -2
	v_mov_b32_e32 v1, 0
	v_mov_b64_e32 v[2:3], 0
	v_mov_b64_e32 v[4:5], 0
	v_mov_b64_e32 v[6:7], 0
	v_mov_b64_e32 v[8:9], 0
	v_mov_b64_e32 v[10:11], 0
	v_mov_b64_e32 v[12:13], 0
	v_mov_b64_e32 v[14:15], 0
	v_mov_b64_e32 v[16:17], 0
	v_mov_b64_e32 v[18:19], 0
	v_mov_b64_e32 v[20:21], 0
	v_mov_b64_e32 v[22:23], 0
	v_mov_b64_e32 v[24:25], 0
	v_mov_b64_e32 v[26:27], 0
	v_mov_b64_e32 v[28:29], 0
	v_mov_b64_e32 v[30:31], 0
	v_mov_b64_e32 v[32:33], 0
	v_mov_b64_e32 v[34:35], 0
	v_mov_b64_e32 v[36:37], 0
	v_mov_b64_e32 v[38:39], 0
	v_mov_b64_e32 v[40:41], 0
	v_mov_b64_e32 v[42:43], 0
	v_mov_b64_e32 v[44:45], 0
	v_mov_b64_e32 v[46:47], 0
	v_mov_b64_e32 v[48:49], 0
	v_mov_b64_e32 v[50:51], 0
	v_mov_b64_e32 v[52:53], 0
	v_mov_b64_e32 v[54:55], 0
	v_mov_b64_e32 v[56:57], 0
	v_mov_b64_e32 v[58:59], 0
	v_mov_b64_e32 v[60:61], 0
	v_mov_b64_e32 v[62:63], 0
	v_mov_b64_e32 v[64:65], 0
	v_mov_b64_e32 v[66:67], 0
	v_mov_b64_e32 v[68:69], 0
	v_mov_b64_e32 v[70:71], 0
	v_mov_b64_e32 v[72:73], 0
	v_mov_b64_e32 v[74:75], 0
	v_mov_b64_e32 v[76:77], 0
	v_mov_b64_e32 v[78:79], 0
	v_mov_b64_e32 v[80:81], 0
	v_mov_b64_e32 v[82:83], 0
	v_mov_b64_e32 v[84:85], 0
	v_mov_b64_e32 v[86:87], 0
	v_mov_b64_e32 v[88:89], 0
	v_mov_b64_e32 v[90:91], 0
	v_mov_b64_e32 v[92:93], 0
	v_mov_b64_e32 v[94:95], 0
	v_mov_b64_e32 v[96:97], 0
	v_mov_b64_e32 v[98:99], 0
	v_mov_b64_e32 v[100:101], 0
	v_mov_b64_e32 v[102:103], 0
	v_mov_b64_e32 v[104:105], 0
	v_mov_b64_e32 v[106:107], 0
	v_mov_b64_e32 v[108:109], 0
	v_mov_b64_e32 v[110:111], 0
	v_mov_b64_e32 v[112:113], 0
	v_mov_b64_e32 v[114:115], 0
	v_mov_b64_e32 v[116:117], 0
	v_mov_b64_e32 v[118:119], 0
	v_mov_b64_e32 v[120:121], 0
	v_mov_b64_e32 v[122:123], 0
	v_mov_b64_e32 v[124:125], 0
	v_mov_b64_e32 v[126:127], 0
	s_nop 0
	s_nop 0
	s_nop 0
	s_nop 0
	s_nop 0
	s_nop 0
	s_nop 0
	s_nop 0
	s_nop 0
	s_nop 0
